# mixers: 92 bit-trick bf16 roundings (bfe+add3) replaced by v_cvt_pk_bf16_f32 before d16_hi LDS writes
# speedup vs baseline: 1.0200x; 1.0032x over previous
.LBB0_870:
	s_nop 6
	v_max_f32_e32 v56, v40, v40
	v_max_f32_e32 v57, v36, v36
	v_max_f32_e32 v56, v57, v56
	v_max3_f32 v56, v28, v32, v56
	v_mov_b32_e32 v57, v0
	s_nop 1
	v_mov_b32_dpp v57, v56 row_ror:8 row_mask:0xf bank_mask:0xf
	v_max_f32_e32 v57, v57, v57
	v_max_f32_e32 v56, v56, v57
	v_mov_b32_e32 v57, v0
	s_nop 1
	v_mov_b32_dpp v57, v56 row_ror:4 row_mask:0xf bank_mask:0xf
	v_max_f32_e32 v57, v57, v57
	v_max_f32_e32 v56, v56, v57
	v_mov_b32_e32 v57, v0
	s_nop 1
	v_mov_b32_dpp v57, v56 row_ror:2 row_mask:0xf bank_mask:0xf
	v_max_f32_e32 v57, v57, v57
	v_max_f32_e32 v56, v56, v57
	v_mov_b32_e32 v57, v0
	s_nop 1
	v_mov_b32_dpp v57, v56 row_ror:1 row_mask:0xf bank_mask:0xf
	v_max3_f32 v82, v80, v56, v57
	v_sub_f32_e32 v28, v28, v82
	v_mul_f32_e32 v28, 0x3fb8aa3b, v28
	v_exp_f32_e32 v63, v28
	v_sub_f32_e32 v28, v32, v82
	v_mul_f32_e32 v28, 0x3fb8aa3b, v28
	v_exp_f32_e32 v61, v28
	v_sub_f32_e32 v28, v36, v82
	v_mul_f32_e32 v28, 0x3fb8aa3b, v28
	v_exp_f32_e32 v59, v28
	v_sub_f32_e32 v28, v40, v82
	v_mul_f32_e32 v28, 0x3fb8aa3b, v28
	v_exp_f32_e32 v57, v28
	v_max_f32_e32 v28, v41, v41
	v_max_f32_e32 v32, v37, v37
	v_max_f32_e32 v28, v32, v28
	v_max3_f32 v28, v29, v33, v28
	v_mov_b32_e32 v32, v0
	v_sub_f32_e32 v56, v80, v82
	v_mul_f32_e32 v56, 0x3fb8aa3b, v56
	v_mov_b32_dpp v32, v28 row_ror:8 row_mask:0xf bank_mask:0xf
	v_max_f32_e32 v32, v32, v32
	v_max_f32_e32 v28, v28, v32
	v_mov_b32_e32 v32, v0
	v_exp_f32_e32 v81, v56
	s_nop 0
	v_mov_b32_dpp v32, v28 row_ror:4 row_mask:0xf bank_mask:0xf
	v_max_f32_e32 v32, v32, v32
	v_max_f32_e32 v28, v28, v32
	v_mov_b32_e32 v32, v0
	s_nop 1
	v_mov_b32_dpp v32, v28 row_ror:2 row_mask:0xf bank_mask:0xf
	v_max_f32_e32 v32, v32, v32
	v_max_f32_e32 v28, v28, v32
	v_mov_b32_e32 v32, v0
	s_nop 1
	v_mov_b32_dpp v32, v28 row_ror:1 row_mask:0xf bank_mask:0xf
	v_max3_f32 v83, v78, v28, v32
	v_sub_f32_e32 v29, v29, v83
	v_mul_f32_e32 v29, 0x3fb8aa3b, v29
	v_exp_f32_e32 v62, v29
	v_sub_f32_e32 v29, v33, v83
	v_mul_f32_e32 v29, 0x3fb8aa3b, v29
	v_exp_f32_e32 v60, v29
	v_sub_f32_e32 v29, v37, v83
	v_mul_f32_e32 v29, 0x3fb8aa3b, v29
	v_exp_f32_e32 v58, v29
	v_sub_f32_e32 v29, v41, v83
	v_sub_f32_e32 v28, v78, v83
	v_mul_f32_e32 v29, 0x3fb8aa3b, v29
	v_mul_f32_e32 v28, 0x3fb8aa3b, v28
	v_exp_f32_e32 v56, v29
	v_exp_f32_e32 v80, v28
	v_pk_add_f32 v[28:29], v[62:63], 0 op_sel_hi:[1,0]
	v_mov_b32_e32 v33, v0
	v_pk_add_f32 v[28:29], v[60:61], v[28:29]
	v_mov_b32_e32 v32, v0
	v_pk_add_f32 v[28:29], v[58:59], v[28:29]
	s_nop 0
	v_pk_add_f32 v[28:29], v[56:57], v[28:29]
	s_nop 1
	v_mov_b32_dpp v33, v29 row_ror:8 row_mask:0xf bank_mask:0xf
	v_mov_b32_dpp v32, v28 row_ror:8 row_mask:0xf bank_mask:0xf
	v_pk_add_f32 v[28:29], v[28:29], v[32:33]
	v_mov_b32_e32 v33, v0
	v_mov_b32_e32 v32, v0
	s_nop 0
	v_mov_b32_dpp v33, v29 row_ror:4 row_mask:0xf bank_mask:0xf
	v_mov_b32_dpp v32, v28 row_ror:4 row_mask:0xf bank_mask:0xf
	v_pk_add_f32 v[28:29], v[28:29], v[32:33]
	v_mov_b32_e32 v33, v0
	v_mov_b32_e32 v32, v0
	s_nop 0
	v_mov_b32_dpp v33, v29 row_ror:2 row_mask:0xf bank_mask:0xf
	v_mov_b32_dpp v32, v28 row_ror:2 row_mask:0xf bank_mask:0xf
	v_pk_add_f32 v[28:29], v[28:29], v[32:33]
	v_mov_b32_e32 v33, v0
	v_mov_b32_e32 v32, v0
	s_nop 0
	v_mov_b32_dpp v33, v29 row_ror:1 row_mask:0xf bank_mask:0xf
	v_mov_b32_dpp v32, v28 row_ror:1 row_mask:0xf bank_mask:0xf
	v_pk_add_f32 v[28:29], v[28:29], v[32:33]
	s_nop 0
	v_pk_fma_f32 v[54:55], v[54:55], v[80:81], v[28:29]
	v_max_f32_e32 v28, v42, v42
	v_max_f32_e32 v29, v38, v38
	v_max_f32_e32 v28, v29, v28
	v_max3_f32 v28, v30, v34, v28
	v_mov_b32_e32 v29, v0
	s_nop 1
	v_mov_b32_dpp v29, v28 row_ror:8 row_mask:0xf bank_mask:0xf
	v_max_f32_e32 v29, v29, v29
	v_max_f32_e32 v28, v28, v29
	v_mov_b32_e32 v29, v0
	s_nop 1
	v_mov_b32_dpp v29, v28 row_ror:4 row_mask:0xf bank_mask:0xf
	v_max_f32_e32 v29, v29, v29
	v_max_f32_e32 v28, v28, v29
	v_mov_b32_e32 v29, v0
	s_nop 1
	v_mov_b32_dpp v29, v28 row_ror:2 row_mask:0xf bank_mask:0xf
	v_max_f32_e32 v29, v29, v29
	v_max_f32_e32 v28, v28, v29
	v_mov_b32_e32 v29, v0
	s_nop 1
	v_mov_b32_dpp v29, v28 row_ror:1 row_mask:0xf bank_mask:0xf
	v_max3_f32 v84, v79, v28, v29
	v_sub_f32_e32 v29, v30, v84
	v_sub_f32_e32 v30, v34, v84
	v_mul_f32_e32 v30, 0x3fb8aa3b, v30
	v_exp_f32_e32 v33, v30
	v_sub_f32_e32 v30, v38, v84
	v_mul_f32_e32 v30, 0x3fb8aa3b, v30
	v_sub_f32_e32 v28, v79, v84
	v_exp_f32_e32 v37, v30
	v_sub_f32_e32 v30, v42, v84
	v_mul_f32_e32 v28, 0x3fb8aa3b, v28
	v_mul_f32_e32 v30, 0x3fb8aa3b, v30
	v_exp_f32_e32 v41, v30
	v_exp_f32_e32 v79, v28
	v_max_f32_e32 v28, v43, v43
	v_max_f32_e32 v30, v39, v39
	v_max_f32_e32 v28, v30, v28
	v_max3_f32 v28, v31, v35, v28
	v_mov_b32_e32 v30, v0
	v_mul_f32_e32 v29, 0x3fb8aa3b, v29
	v_exp_f32_e32 v29, v29
	v_mov_b32_dpp v30, v28 row_ror:8 row_mask:0xf bank_mask:0xf
	v_max_f32_e32 v30, v30, v30
	v_max_f32_e32 v28, v28, v30
	v_mov_b32_e32 v30, v0
	v_mov_b32_e32 v34, v0
	s_nop 0
	v_mov_b32_dpp v30, v28 row_ror:4 row_mask:0xf bank_mask:0xf
	v_max_f32_e32 v30, v30, v30
	v_max_f32_e32 v28, v28, v30
	v_mov_b32_e32 v30, v0
	s_nop 1
	v_mov_b32_dpp v30, v28 row_ror:2 row_mask:0xf bank_mask:0xf
	v_max_f32_e32 v30, v30, v30
	v_max_f32_e32 v28, v28, v30
	v_mov_b32_e32 v30, v0
	s_nop 1
	v_mov_b32_dpp v30, v28 row_ror:1 row_mask:0xf bank_mask:0xf
	v_max3_f32 v42, v1, v28, v30
	v_sub_f32_e32 v1, v1, v42
	v_mul_f32_e32 v1, 0x3fb8aa3b, v1
	v_sub_f32_e32 v28, v31, v42
	v_exp_f32_e32 v78, v1
	v_mul_f32_e32 v28, 0x3fb8aa3b, v28
	v_cvt_pk_bf16_f32 v1, v63, v63
	v_exp_f32_e32 v28, v28
	ds_write_b16_d16_hi v74, v1 offset:18432
	v_cvt_pk_bf16_f32 v1, v62, v62
	ds_write_b16_d16_hi v74, v1 offset:18576
	v_cvt_pk_bf16_f32 v1, v29, v29
	ds_write_b16_d16_hi v74, v1 offset:18720
	v_cvt_pk_bf16_f32 v1, v28, v28
	v_sub_f32_e32 v30, v35, v42
	ds_write_b16_d16_hi v74, v1 offset:18864
	v_mul_f32_e32 v30, 0x3fb8aa3b, v30
	v_cvt_pk_bf16_f32 v1, v61, v61
	v_exp_f32_e32 v32, v30
	ds_write_b16_d16_hi v74, v1 offset:18464
	v_cvt_pk_bf16_f32 v1, v60, v60
	ds_write_b16_d16_hi v74, v1 offset:18608
	v_cvt_pk_bf16_f32 v1, v33, v33
	ds_write_b16_d16_hi v74, v1 offset:18752
	v_sub_f32_e32 v30, v39, v42
	v_cvt_pk_bf16_f32 v1, v32, v32
	v_mul_f32_e32 v30, 0x3fb8aa3b, v30
	ds_write_b16_d16_hi v74, v1 offset:18896
	v_exp_f32_e32 v36, v30
	v_sub_f32_e32 v30, v43, v42
	v_cvt_pk_bf16_f32 v1, v59, v59
	v_mul_f32_e32 v30, 0x3fb8aa3b, v30
	ds_write_b16_d16_hi v74, v1 offset:18496
	v_exp_f32_e32 v40, v30
	v_cvt_pk_bf16_f32 v1, v58, v58
	v_pk_add_f32 v[30:31], v[28:29], 0 op_sel_hi:[1,0]
	ds_write_b16_d16_hi v74, v1 offset:18640
	v_pk_add_f32 v[30:31], v[32:33], v[30:31]
	v_cvt_pk_bf16_f32 v1, v37, v37
	v_pk_add_f32 v[30:31], v[36:37], v[30:31]
	ds_write_b16_d16_hi v74, v1 offset:18784
	v_pk_add_f32 v[30:31], v[40:41], v[30:31]
	v_mov_b32_e32 v35, v0
	v_cvt_pk_bf16_f32 v1, v36, v36
	v_mov_b32_dpp v34, v30 row_ror:8 row_mask:0xf bank_mask:0xf
	v_mov_b32_dpp v35, v31 row_ror:8 row_mask:0xf bank_mask:0xf
	ds_write_b16_d16_hi v74, v1 offset:18928
	v_pk_add_f32 v[30:31], v[30:31], v[34:35]
	v_mov_b32_e32 v35, v0
	v_mov_b32_e32 v34, v0
	v_cvt_pk_bf16_f32 v1, v57, v57
	v_mov_b32_dpp v35, v31 row_ror:4 row_mask:0xf bank_mask:0xf
	v_mov_b32_dpp v34, v30 row_ror:4 row_mask:0xf bank_mask:0xf
	ds_write_b16_d16_hi v74, v1 offset:18528
	v_pk_add_f32 v[30:31], v[30:31], v[34:35]
	v_mov_b32_e32 v35, v0
	v_mov_b32_e32 v34, v0
	v_cvt_pk_bf16_f32 v1, v56, v56
	v_mov_b32_dpp v35, v31 row_ror:2 row_mask:0xf bank_mask:0xf
	v_mov_b32_dpp v34, v30 row_ror:2 row_mask:0xf bank_mask:0xf
	ds_write_b16_d16_hi v74, v1 offset:18672
	v_pk_add_f32 v[30:31], v[30:31], v[34:35]
	v_mov_b32_e32 v35, v0
	v_mov_b32_e32 v34, v0
	v_cvt_pk_bf16_f32 v1, v41, v41
	v_mov_b32_dpp v35, v31 row_ror:1 row_mask:0xf bank_mask:0xf
	v_mov_b32_dpp v34, v30 row_ror:1 row_mask:0xf bank_mask:0xf
	ds_write_b16_d16_hi v74, v1 offset:18816
	v_pk_add_f32 v[30:31], v[30:31], v[34:35]
	v_cvt_pk_bf16_f32 v1, v40, v40
	v_pk_fma_f32 v[2:3], v[2:3], v[78:79], v[30:31]
	v_mov_b32_e32 v30, v79
	v_mov_b32_e32 v31, v78
	v_mov_b32_e32 v34, v81
	v_mov_b32_e32 v35, v80
	ds_write_b16_d16_hi v74, v1 offset:18960
	v_pk_mul_f32 v[14:15], v[14:15], v[30:31]
	v_pk_mul_f32 v[12:13], v[12:13], v[34:35]
	v_pk_mul_f32 v[18:19], v[18:19], v[30:31]
	v_pk_mul_f32 v[16:17], v[16:17], v[34:35]
	v_pk_mul_f32 v[22:23], v[22:23], v[30:31]
	v_pk_mul_f32 v[20:21], v[20:21], v[34:35]
	v_pk_mul_f32 v[26:27], v[26:27], v[30:31]
	v_pk_mul_f32 v[24:25], v[24:25], v[34:35]
	ds_read_b128 v[28:31], v75 offset:18432
	ds_read_b128 v[32:35], v75 offset:18496
	ds_read_b128 v[36:39], v77 offset:9216
	s_waitcnt lgkmcnt(0)
	v_mfma_f32_16x16x32_bf16 v[12:15], v[28:31], v[36:39], v[12:15]
	ds_read_b128 v[36:39], v77 offset:9280
	v_mov_b32_e32 v1, v42
	v_mov_b32_e32 v79, v84
	s_waitcnt lgkmcnt(0)
	v_mfma_f32_16x16x32_bf16 v[12:15], v[32:35], v[36:39], v[12:15]
	ds_read_b128 v[36:39], v77 offset:11520
	v_mov_b32_e32 v80, v82
	v_mov_b32_e32 v78, v83
	s_waitcnt lgkmcnt(0)
	v_mfma_f32_16x16x32_bf16 v[16:19], v[28:31], v[36:39], v[16:19]
	ds_read_b128 v[36:39], v77 offset:11584
	s_waitcnt lgkmcnt(0)
	v_mfma_f32_16x16x32_bf16 v[16:19], v[32:35], v[36:39], v[16:19]
	ds_read_b128 v[36:39], v77 offset:13824
	s_waitcnt lgkmcnt(0)
	v_mfma_f32_16x16x32_bf16 v[20:23], v[28:31], v[36:39], v[20:23]
	ds_read_b128 v[36:39], v77 offset:13888
	s_waitcnt lgkmcnt(0)
	v_mfma_f32_16x16x32_bf16 v[20:23], v[32:35], v[36:39], v[20:23]
	ds_read_b128 v[36:39], v77 offset:16128
	s_waitcnt lgkmcnt(0)
	v_mfma_f32_16x16x32_bf16 v[24:27], v[28:31], v[36:39], v[24:27]
	ds_read_b128 v[28:31], v77 offset:16192
	s_waitcnt lgkmcnt(0)
	s_barrier
	v_mfma_f32_16x16x32_bf16 v[24:27], v[32:35], v[28:31], v[24:27]

.LBB0_879:
	s_waitcnt vmcnt(0)
	v_bfe_u32 v60, v36, 16, 1
	v_add3_u32 v36, v36, v60, s33
	ds_write_b16_d16_hi v73, v36 offset:9216
	v_cvt_pk_bf16_f32 v36, v37, v37
	ds_write_b16_d16_hi v73, v36 offset:9360
	v_cvt_pk_bf16_f32 v36, v38, v38
	ds_write_b16_d16_hi v73, v36 offset:9504
	v_cvt_pk_bf16_f32 v36, v39, v39
	ds_write_b16_d16_hi v73, v36 offset:9648
	v_cvt_pk_bf16_f32 v36, v40, v40
	ds_write_b16_d16_hi v73, v36 offset:9792
	v_cvt_pk_bf16_f32 v36, v41, v41
	ds_write_b16_d16_hi v73, v36 offset:9936
	v_cvt_pk_bf16_f32 v36, v42, v42
	ds_write_b16_d16_hi v73, v36 offset:10080
	v_cvt_pk_bf16_f32 v36, v43, v43
	ds_write_b16_d16_hi v73, v36 offset:10224
	v_bfe_u32 v36, v28, 16, 1
	v_add3_u32 v28, v28, v36, s33
	ds_write_b16_d16_hi v73, v28 offset:10368
	v_cvt_pk_bf16_f32 v28, v29, v29
	ds_write_b16_d16_hi v73, v28 offset:10512
	v_cvt_pk_bf16_f32 v28, v30, v30
	ds_write_b16_d16_hi v73, v28 offset:10656
	v_cvt_pk_bf16_f32 v28, v31, v31
	ds_write_b16_d16_hi v73, v28 offset:10800
	v_cvt_pk_bf16_f32 v28, v32, v32
	ds_write_b16_d16_hi v73, v28 offset:10944
	v_cvt_pk_bf16_f32 v28, v33, v33
	ds_write_b16_d16_hi v73, v28 offset:11088
	v_cvt_pk_bf16_f32 v28, v34, v34
	ds_write_b16_d16_hi v73, v28 offset:11232
	v_bfe_u32 v28, v35, 16, 1
	v_add3_u32 v28, v35, v28, s33
	ds_write_b16_d16_hi v73, v28 offset:11376
	s_mov_b64 s[6:7], -1
	s_and_b64 vcc, exec, s[14:15]
	v_lshl_add_u64 v[56:57], v[50:51], 0, v[56:57]
	s_cbranch_vccz .LBB0_881
	global_load_dwordx4 v[28:31], v[56:57], off offset:16
	global_load_dwordx4 v[32:35], v[56:57], off
	s_mov_b64 s[6:7], 0
	s_waitcnt vmcnt(1)
	v_mov_b32_e32 v36, v31
	v_mov_b32_e32 v38, v28
	s_waitcnt vmcnt(0)
	v_mov_b32_e32 v60, v34
	v_mov_b32_e32 v62, v32

.LBB0_915:
	s_movk_i32 s0, 0x90
	v_lshlrev_b32_e32 v68, 1, v77
	s_waitcnt vmcnt(0)
	v_mul_lo_u32 v4, v90, s0
	v_cvt_pk_bf16_f32 v1, v2, v2
	v_add_u32_e32 v93, v68, v4
	ds_write_b16_d16_hi v93, v1 offset:36864
	v_or_b32_e32 v94, 1, v90
	v_cndmask_b32_e64 v1, 0, 1, s[10:11]
	v_cmp_ne_u32_e64 s[4:5], 1, v1
	s_andn2_b64 vcc, exec, s[10:11]
	v_ashrrev_i32_e32 v95, 31, v94
	s_cbranch_vccnz .LBB0_917
	v_lshlrev_b64 v[4:5], 8, v[94:95]
	v_lshl_add_u64 v[4:5], v[14:15], 0, v[4:5]
	global_load_dword v3, v[4:5], off

.LBB0_945:
	s_waitcnt vmcnt(0)
	v_cvt_pk_bf16_f32 v1, v25, v25
	ds_write_b16_d16_hi v93, v1 offset:37392
	v_mul_hi_i32 v1, v66, s2
	v_lshrrev_b32_e32 v14, 31, v1
	v_ashrrev_i32_e32 v1, 2, v1
	v_add_u32_e32 v1, v1, v14
	s_movk_i32 s0, 0xffe8
	v_mad_u64_u32 v[70:71], s[0:1], v1, s0, v[66:67]
	v_cmp_gt_i32_e32 vcc, 8, v70
	v_cmp_lt_i32_e64 s[0:1], 7, v70
	s_and_saveexec_b64 s[4:5], s[0:1]
	s_xor_b64 s[4:5], exec, s[4:5]
	s_cbranch_execz .LBB0_951
	v_cmp_lt_u32_e64 s[0:1], 15, v70
	s_lshl_b32 s6, s21, 6
	s_and_saveexec_b64 s[8:9], s[0:1]
	s_xor_b64 s[0:1], exec, s[8:9]
	s_add_i32 s7, s6, 0x580
	s_or_saveexec_b64 s[0:1], s[0:1]
	v_mov_b32_e32 v14, s7
	s_xor_b64 exec, exec, s[0:1]
	s_addk_i32 s6, 0x540
	v_mov_b32_e32 v14, s6
	s_or_b64 exec, exec, s[0:1]

.LBB0_1033:
	ds_read_b32 v1, v0 offset:46332
	ds_read_b128 v[66:69], v115 offset:18432
	ds_read_b128 v[70:73], v127 offset:46592
	ds_read_b128 v[74:77], v127 offset:46608
	s_sub_i32 s76, s76, 64
	s_and_b64 vcc, exec, s[0:1]
	s_waitcnt lgkmcnt(2)
	v_and_b32_e32 v79, 0xffff0000, v66
	v_lshlrev_b32_e32 v78, 16, v66
	s_waitcnt lgkmcnt(1)
	v_pk_mul_f32 v[70:71], v[70:71], v[78:79]
	v_and_b32_e32 v79, 0xffff0000, v67
	v_lshlrev_b32_e32 v78, 16, v67
	v_pk_mul_f32 v[66:67], v[72:73], v[78:79]
	v_and_b32_e32 v73, 0xffff0000, v68
	v_lshlrev_b32_e32 v72, 16, v68
	s_waitcnt lgkmcnt(0)
	v_pk_mul_f32 v[72:73], v[74:75], v[72:73]
	v_and_b32_e32 v75, 0xffff0000, v69
	v_lshlrev_b32_e32 v74, 16, v69
	v_pk_mul_f32 v[68:69], v[76:77], v[74:75]
	v_bfe_u32 v79, v72, 16, 1
	v_cvt_pk_bf16_f32 v82, v66, v66
	v_cvt_pk_bf16_f32 v83, v67, v67
	v_cvt_pk_bf16_f32 v84, v68, v68
	v_cvt_pk_bf16_f32 v85, v69, v69
	v_cvt_pk_bf16_f32 v81, v70, v70
	v_cvt_pk_bf16_f32 v80, v71, v71
	v_add3_u32 v79, v72, v79, s33
	v_cvt_pk_bf16_f32 v89, v73, v73
	ds_read_b128 v[66:69], v115 offset:18496
	ds_read_b128 v[70:73], v127 offset:46720
	v_mul_f32_e32 v1, 0x3fb8aa3b, v1
	s_waitcnt lgkmcnt(1)
	v_and_b32_e32 v75, 0xffff0000, v66
	v_lshlrev_b32_e32 v74, 16, v66
	s_waitcnt lgkmcnt(0)
	v_pk_mul_f32 v[74:75], v[70:71], v[74:75]
	v_and_b32_e32 v71, 0xffff0000, v67
	v_lshlrev_b32_e32 v70, 16, v67
	v_pk_mul_f32 v[66:67], v[72:73], v[70:71]
	ds_read_b128 v[70:73], v127 offset:46736
	v_and_b32_e32 v77, 0xffff0000, v68
	v_lshlrev_b32_e32 v76, 16, v68
	s_waitcnt lgkmcnt(0)
	v_pk_mul_f32 v[70:71], v[70:71], v[76:77]
	v_and_b32_e32 v77, 0xffff0000, v69
	v_lshlrev_b32_e32 v76, 16, v69
	v_pk_mul_f32 v[68:69], v[72:73], v[76:77]
	v_cvt_pk_bf16_f32 v143, v66, v66
	v_cvt_pk_bf16_f32 v144, v67, v67
	v_cvt_pk_bf16_f32 v145, v68, v68
	v_cvt_pk_bf16_f32 v146, v69, v69
	v_cvt_pk_bf16_f32 v106, v70, v70
	v_cvt_pk_bf16_f32 v147, v71, v71
	v_exp_f32_e32 v78, v1
	ds_read_b128 v[66:69], v141 offset:27648
	v_perm_b32 v73, v85, v84, s3
	v_perm_b32 v71, v83, v82, s3
	v_perm_b32 v72, v89, v79, s3
	v_perm_b32 v70, v80, v81, s3
	v_cvt_pk_bf16_f32 v142, v74, v74
	v_cvt_pk_bf16_f32 v107, v75, v75
	v_pk_mul_f32 v[4:5], v[4:5], v[78:79] op_sel_hi:[1,0]
	v_pk_mul_f32 v[2:3], v[2:3], v[78:79] op_sel_hi:[1,0]
	ds_read_b128 v[74:77], v141 offset:27712
	v_pk_mul_f32 v[8:9], v[8:9], v[78:79] op_sel_hi:[1,0]
	s_waitcnt lgkmcnt(1)
	v_mfma_f32_16x16x32_bf16 v[2:5], v[70:73], v[66:69], v[2:5]
	v_perm_b32 v69, v146, v145, s3
	v_perm_b32 v67, v144, v143, s3
	v_perm_b32 v68, v147, v106, s3
	v_perm_b32 v66, v107, v142, s3
	v_pk_mul_f32 v[6:7], v[6:7], v[78:79] op_sel_hi:[1,0]
	v_pk_mul_f32 v[12:13], v[12:13], v[78:79] op_sel_hi:[1,0]
	s_waitcnt lgkmcnt(0)
	v_mfma_f32_16x16x32_bf16 v[2:5], v[66:69], v[74:77], v[2:5]
	ds_read_b128 v[74:77], v141 offset:29952
	v_pk_mul_f32 v[10:11], v[10:11], v[78:79] op_sel_hi:[1,0]
	v_pk_mul_f32 v[24:25], v[24:25], v[78:79] op_sel_hi:[1,0]
	s_waitcnt lgkmcnt(0)
	v_mfma_f32_16x16x32_bf16 v[6:9], v[70:73], v[74:77], v[6:9]
	ds_read_b128 v[74:77], v141 offset:30016
	s_nop 1
	v_pk_mul_f32 v[22:23], v[22:23], v[78:79] op_sel_hi:[1,0]
	s_waitcnt lgkmcnt(0)
	v_mfma_f32_16x16x32_bf16 v[6:9], v[66:69], v[74:77], v[6:9]
	ds_read_b128 v[74:77], v141 offset:32256
	v_cvt_pk_bf16_f32 v1, v2, v2
	s_waitcnt lgkmcnt(0)
	v_mfma_f32_16x16x32_bf16 v[10:13], v[70:73], v[74:77], v[10:13]
	ds_read_b128 v[74:77], v141 offset:32320
	s_waitcnt lgkmcnt(0)
	v_mfma_f32_16x16x32_bf16 v[10:13], v[66:69], v[74:77], v[10:13]
	ds_read_b128 v[74:77], v141 offset:34560
	s_waitcnt lgkmcnt(0)
	v_mfma_f32_16x16x32_bf16 v[22:25], v[70:73], v[74:77], v[22:25]
	ds_read_b128 v[70:73], v141 offset:34624
	s_waitcnt lgkmcnt(0)
	s_barrier
	ds_write_b16_d16_hi v93, v1 offset:36864
	v_cvt_pk_bf16_f32 v1, v3, v3
	ds_write_b16_d16_hi v93, v1 offset:37008
	v_cvt_pk_bf16_f32 v1, v4, v4
	ds_write_b16_d16_hi v93, v1 offset:37152
	v_cvt_pk_bf16_f32 v1, v5, v5
	ds_write_b16_d16_hi v93, v1 offset:37296
	v_cvt_pk_bf16_f32 v1, v6, v6
	ds_write_b16_d16_hi v93, v1 offset:36896
	v_cvt_pk_bf16_f32 v1, v7, v7
	ds_write_b16_d16_hi v93, v1 offset:37040
	v_cvt_pk_bf16_f32 v1, v8, v8
	ds_write_b16_d16_hi v93, v1 offset:37184
	v_cvt_pk_bf16_f32 v1, v9, v9
	ds_write_b16_d16_hi v93, v1 offset:37328
	v_cvt_pk_bf16_f32 v1, v10, v10
	ds_write_b16_d16_hi v93, v1 offset:36928
	v_cvt_pk_bf16_f32 v1, v11, v11
	v_mfma_f32_16x16x32_bf16 v[22:25], v[66:69], v[70:73], v[22:25]
	ds_write_b16_d16_hi v93, v1 offset:37072
	v_cvt_pk_bf16_f32 v1, v12, v12
	ds_write_b16_d16_hi v93, v1 offset:37216
	v_cvt_pk_bf16_f32 v1, v13, v13
	ds_write_b16_d16_hi v93, v1 offset:37360
	s_nop 0
	s_nop 1
	v_cvt_pk_bf16_f32 v1, v22, v22
	ds_write_b16_d16_hi v93, v1 offset:36960
	v_cvt_pk_bf16_f32 v1, v23, v23
	ds_write_b16_d16_hi v93, v1 offset:37104
	v_cvt_pk_bf16_f32 v1, v24, v24
	ds_write_b16_d16_hi v93, v1 offset:37248
	v_bfe_u32 v1, v25, 16, 1
	v_add3_u32 v1, v25, v1, s33
	ds_write_b16_d16_hi v93, v1 offset:37392
	s_cbranch_vccnz .LBB0_1035
	s_mov_b32 s78, s97
	s_and_saveexec_b64 s[0:1], s[4:5]
	s_xor_b64 s[0:1], exec, s[0:1]
	s_cbranch_execnz .Lssd0_w3back
	s_branch .LBB0_985

.LBB0_2365:
	s_waitcnt vmcnt(0)
	v_bfe_u32 v60, v36, 16, 1
	v_add3_u32 v36, v36, v60, s78
	ds_write_b16_d16_hi v73, v36 offset:9216
	v_cvt_pk_bf16_f32 v36, v37, v37
	ds_write_b16_d16_hi v73, v36 offset:9360
	v_cvt_pk_bf16_f32 v36, v38, v38
	ds_write_b16_d16_hi v73, v36 offset:9504
	v_cvt_pk_bf16_f32 v36, v39, v39
	ds_write_b16_d16_hi v73, v36 offset:9648
	v_cvt_pk_bf16_f32 v36, v40, v40
	ds_write_b16_d16_hi v73, v36 offset:9792
	v_cvt_pk_bf16_f32 v36, v41, v41
	ds_write_b16_d16_hi v73, v36 offset:9936
	v_cvt_pk_bf16_f32 v36, v42, v42
	ds_write_b16_d16_hi v73, v36 offset:10080
	v_cvt_pk_bf16_f32 v36, v43, v43
	ds_write_b16_d16_hi v73, v36 offset:10224
	v_bfe_u32 v36, v28, 16, 1
	v_add3_u32 v28, v28, v36, s78
	ds_write_b16_d16_hi v73, v28 offset:10368
	v_cvt_pk_bf16_f32 v28, v29, v29
	ds_write_b16_d16_hi v73, v28 offset:10512
	v_cvt_pk_bf16_f32 v28, v30, v30
	ds_write_b16_d16_hi v73, v28 offset:10656
	v_cvt_pk_bf16_f32 v28, v31, v31
	ds_write_b16_d16_hi v73, v28 offset:10800
	v_cvt_pk_bf16_f32 v28, v32, v32
	ds_write_b16_d16_hi v73, v28 offset:10944
	v_cvt_pk_bf16_f32 v28, v33, v33
	ds_write_b16_d16_hi v73, v28 offset:11088
	v_cvt_pk_bf16_f32 v28, v34, v34
	ds_write_b16_d16_hi v73, v28 offset:11232
	v_bfe_u32 v28, v35, 16, 1
	v_add3_u32 v28, v35, v28, s78
	ds_write_b16_d16_hi v73, v28 offset:11376
	s_mov_b64 s[6:7], -1
	s_and_b64 vcc, exec, s[14:15]
	v_lshl_add_u64 v[56:57], v[50:51], 0, v[56:57]
	s_cbranch_vccz .LBB0_2367
	global_load_dwordx4 v[28:31], v[56:57], off offset:16
	global_load_dwordx4 v[32:35], v[56:57], off
	s_mov_b64 s[6:7], 0
	s_waitcnt vmcnt(1)
	v_mov_b32_e32 v36, v31
	v_mov_b32_e32 v38, v28
	s_waitcnt vmcnt(0)
	v_mov_b32_e32 v60, v34
	v_mov_b32_e32 v62, v32

.LBB0_2401:
	v_lshlrev_b32_e32 v68, 1, v77
	s_waitcnt vmcnt(0)
	v_mul_lo_u32 v4, v90, s63
	v_cvt_pk_bf16_f32 v1, v2, v2
	v_add_u32_e32 v93, v68, v4
	ds_write_b16_d16_hi v93, v1 offset:36864
	v_or_b32_e32 v94, 1, v90
	v_cndmask_b32_e64 v1, 0, 1, s[12:13]
	v_cmp_ne_u32_e64 s[4:5], 1, v1
	s_andn2_b64 vcc, exec, s[12:13]
	v_ashrrev_i32_e32 v95, 31, v94
	s_cbranch_vccnz .LBB0_2403
	v_lshlrev_b64 v[4:5], 8, v[94:95]
	v_lshl_add_u64 v[4:5], v[14:15], 0, v[4:5]
	global_load_dword v3, v[4:5], off

.LBB0_2431:
	s_waitcnt vmcnt(0)
	v_cvt_pk_bf16_f32 v1, v29, v29
	ds_write_b16_d16_hi v93, v1 offset:37392
	v_mul_hi_i32 v1, v66, s79
	v_lshrrev_b32_e32 v14, 31, v1
	v_ashrrev_i32_e32 v1, 2, v1
	v_add_u32_e32 v1, v1, v14
	v_mad_u64_u32 v[70:71], s[0:1], v1, s71, v[66:67]
	v_cmp_gt_i32_e32 vcc, 8, v70
	v_cmp_lt_i32_e64 s[0:1], 7, v70
	s_and_saveexec_b64 s[4:5], s[0:1]
	s_xor_b64 s[4:5], exec, s[4:5]
	s_cbranch_execz .LBB0_2437
	v_cmp_lt_u32_e64 s[0:1], 15, v70
	s_lshl_b32 s6, s11, 6
	s_and_saveexec_b64 s[8:9], s[0:1]
	s_xor_b64 s[0:1], exec, s[8:9]
	s_add_i32 s7, s6, 0x580
	s_or_saveexec_b64 s[0:1], s[0:1]
	v_mov_b32_e32 v14, s7
	s_xor_b64 exec, exec, s[0:1]
	s_addk_i32 s6, 0x540
	v_mov_b32_e32 v14, s6
	s_or_b64 exec, exec, s[0:1]

.LBB0_2519:
	ds_read_b32 v1, v0 offset:46332
	ds_read_b128 v[66:69], v115 offset:18432
	ds_read_b128 v[70:73], v128 offset:46592
	ds_read_b128 v[74:77], v128 offset:46608
	s_sub_i32 s84, s84, 64
	s_and_b64 vcc, exec, s[0:1]
	s_waitcnt lgkmcnt(2)
	v_and_b32_e32 v79, 0xffff0000, v66
	v_lshlrev_b32_e32 v78, 16, v66
	s_waitcnt lgkmcnt(1)
	v_pk_mul_f32 v[70:71], v[70:71], v[78:79]
	v_and_b32_e32 v79, 0xffff0000, v67
	v_lshlrev_b32_e32 v78, 16, v67
	v_pk_mul_f32 v[66:67], v[72:73], v[78:79]
	v_and_b32_e32 v73, 0xffff0000, v68
	v_lshlrev_b32_e32 v72, 16, v68
	s_waitcnt lgkmcnt(0)
	v_pk_mul_f32 v[72:73], v[74:75], v[72:73]
	v_and_b32_e32 v75, 0xffff0000, v69
	v_lshlrev_b32_e32 v74, 16, v69
	v_pk_mul_f32 v[68:69], v[76:77], v[74:75]
	v_bfe_u32 v79, v72, 16, 1
	v_cvt_pk_bf16_f32 v82, v66, v66
	v_cvt_pk_bf16_f32 v83, v67, v67
	v_cvt_pk_bf16_f32 v84, v68, v68
	v_cvt_pk_bf16_f32 v85, v69, v69
	v_cvt_pk_bf16_f32 v81, v70, v70
	v_cvt_pk_bf16_f32 v80, v71, v71
	v_add3_u32 v79, v72, v79, s78
	v_cvt_pk_bf16_f32 v89, v73, v73
	ds_read_b128 v[66:69], v115 offset:18496
	ds_read_b128 v[70:73], v128 offset:46720
	v_mul_f32_e32 v1, 0x3fb8aa3b, v1
	s_waitcnt lgkmcnt(1)
	v_and_b32_e32 v75, 0xffff0000, v66
	v_lshlrev_b32_e32 v74, 16, v66
	s_waitcnt lgkmcnt(0)
	v_pk_mul_f32 v[74:75], v[70:71], v[74:75]
	v_and_b32_e32 v71, 0xffff0000, v67
	v_lshlrev_b32_e32 v70, 16, v67
	v_pk_mul_f32 v[66:67], v[72:73], v[70:71]
	ds_read_b128 v[70:73], v128 offset:46736
	v_and_b32_e32 v77, 0xffff0000, v68
	v_lshlrev_b32_e32 v76, 16, v68
	s_waitcnt lgkmcnt(0)
	v_pk_mul_f32 v[70:71], v[70:71], v[76:77]
	v_and_b32_e32 v77, 0xffff0000, v69
	v_lshlrev_b32_e32 v76, 16, v69
	v_pk_mul_f32 v[68:69], v[72:73], v[76:77]
	v_cvt_pk_bf16_f32 v144, v66, v66
	v_cvt_pk_bf16_f32 v145, v67, v67
	v_cvt_pk_bf16_f32 v146, v68, v68
	v_cvt_pk_bf16_f32 v147, v69, v69
	v_cvt_pk_bf16_f32 v106, v70, v70
	v_cvt_pk_bf16_f32 v148, v71, v71
	v_exp_f32_e32 v78, v1
	ds_read_b128 v[66:69], v142 offset:27648
	v_perm_b32 v73, v85, v84, s3
	v_perm_b32 v71, v83, v82, s3
	v_perm_b32 v72, v89, v79, s3
	v_perm_b32 v70, v80, v81, s3
	v_cvt_pk_bf16_f32 v143, v74, v74
	v_cvt_pk_bf16_f32 v107, v75, v75
	v_pk_mul_f32 v[4:5], v[4:5], v[78:79] op_sel_hi:[1,0]
	v_pk_mul_f32 v[2:3], v[2:3], v[78:79] op_sel_hi:[1,0]
	ds_read_b128 v[74:77], v142 offset:27712
	v_pk_mul_f32 v[8:9], v[8:9], v[78:79] op_sel_hi:[1,0]
	s_waitcnt lgkmcnt(1)
	v_mfma_f32_16x16x32_bf16 v[2:5], v[70:73], v[66:69], v[2:5]
	v_perm_b32 v69, v147, v146, s3
	v_perm_b32 v67, v145, v144, s3
	v_perm_b32 v68, v148, v106, s3
	v_perm_b32 v66, v107, v143, s3
	v_pk_mul_f32 v[6:7], v[6:7], v[78:79] op_sel_hi:[1,0]
	v_pk_mul_f32 v[12:13], v[12:13], v[78:79] op_sel_hi:[1,0]
	s_waitcnt lgkmcnt(0)
	v_mfma_f32_16x16x32_bf16 v[2:5], v[66:69], v[74:77], v[2:5]
	ds_read_b128 v[74:77], v142 offset:29952
	v_pk_mul_f32 v[10:11], v[10:11], v[78:79] op_sel_hi:[1,0]
	v_pk_mul_f32 v[28:29], v[28:29], v[78:79] op_sel_hi:[1,0]
	s_waitcnt lgkmcnt(0)
	v_mfma_f32_16x16x32_bf16 v[6:9], v[70:73], v[74:77], v[6:9]
	ds_read_b128 v[74:77], v142 offset:30016
	s_nop 1
	v_pk_mul_f32 v[26:27], v[26:27], v[78:79] op_sel_hi:[1,0]
	s_waitcnt lgkmcnt(0)
	v_mfma_f32_16x16x32_bf16 v[6:9], v[66:69], v[74:77], v[6:9]
	ds_read_b128 v[74:77], v142 offset:32256
	v_cvt_pk_bf16_f32 v1, v2, v2
	s_waitcnt lgkmcnt(0)
	v_mfma_f32_16x16x32_bf16 v[10:13], v[70:73], v[74:77], v[10:13]
	ds_read_b128 v[74:77], v142 offset:32320
	s_waitcnt lgkmcnt(0)
	v_mfma_f32_16x16x32_bf16 v[10:13], v[66:69], v[74:77], v[10:13]
	ds_read_b128 v[74:77], v142 offset:34560
	s_waitcnt lgkmcnt(0)
	v_mfma_f32_16x16x32_bf16 v[26:29], v[70:73], v[74:77], v[26:29]
	ds_read_b128 v[70:73], v142 offset:34624
	s_waitcnt lgkmcnt(0)
	s_barrier
	ds_write_b16_d16_hi v93, v1 offset:36864
	v_cvt_pk_bf16_f32 v1, v3, v3
	ds_write_b16_d16_hi v93, v1 offset:37008
	v_cvt_pk_bf16_f32 v1, v4, v4
	ds_write_b16_d16_hi v93, v1 offset:37152
	v_cvt_pk_bf16_f32 v1, v5, v5
	ds_write_b16_d16_hi v93, v1 offset:37296
	v_cvt_pk_bf16_f32 v1, v6, v6
	ds_write_b16_d16_hi v93, v1 offset:36896
	v_cvt_pk_bf16_f32 v1, v7, v7
	ds_write_b16_d16_hi v93, v1 offset:37040
	v_cvt_pk_bf16_f32 v1, v8, v8
	ds_write_b16_d16_hi v93, v1 offset:37184
	v_cvt_pk_bf16_f32 v1, v9, v9
	ds_write_b16_d16_hi v93, v1 offset:37328
	v_cvt_pk_bf16_f32 v1, v10, v10
	ds_write_b16_d16_hi v93, v1 offset:36928
	v_cvt_pk_bf16_f32 v1, v11, v11
	v_mfma_f32_16x16x32_bf16 v[26:29], v[66:69], v[70:73], v[26:29]
	ds_write_b16_d16_hi v93, v1 offset:37072
	v_cvt_pk_bf16_f32 v1, v12, v12
	ds_write_b16_d16_hi v93, v1 offset:37216
	v_cvt_pk_bf16_f32 v1, v13, v13
	ds_write_b16_d16_hi v93, v1 offset:37360
	s_nop 0
	s_nop 1
	v_cvt_pk_bf16_f32 v1, v26, v26
	ds_write_b16_d16_hi v93, v1 offset:36960
	v_cvt_pk_bf16_f32 v1, v27, v27
	ds_write_b16_d16_hi v93, v1 offset:37104
	v_cvt_pk_bf16_f32 v1, v28, v28
	ds_write_b16_d16_hi v93, v1 offset:37248
	v_bfe_u32 v1, v29, 16, 1
	v_add3_u32 v1, v29, v1, s78
	ds_write_b16_d16_hi v93, v1 offset:37392
	s_cbranch_vccnz .LBB0_2521
	s_mov_b32 s71, s73
	s_and_saveexec_b64 s[0:1], s[4:5]
	s_xor_b64 s[0:1], exec, s[0:1]
	s_cbranch_execnz .Lssd1_w3back
	s_branch .LBB0_2471
